# P1 adaLN table build with dwordx4 loads (4 columns per thread, 2 load round trips instead of 4)
# speedup vs baseline: 1.0033x; 1.0033x over previous
; __device__ __forceinline__ void p1_rows(const Params& P, LAS unsigned char* lds, int G) {
;     ...
;     for (int idx = tid; idx < 2 * DM; idx += NTHREADS) { const int b = idx >> 11, col = idx & (DM - 1);
;         float sh = P.b_ada[col], sc = P.b_ada[DM + col];
;         for (int ks = 0; ks < KS_ADA; ++ks) { sh += adap[(size_t)(ks * 2 + b) * NADA + col]; sc += adap[(size_t)(ks * 2 + b) * NADA + DM + col]; }
;         TA[idx] = P.g_pre_mix[col] * (1.0f + sc); TC[idx] = sh; }
.LBB0_156:
	s_or_b64 exec, exec, s[4:5]
	v_mov_b32_e32 v8, v168
	s_movk_i32 s4, 0x1000
	s_waitcnt lgkmcnt(0)
	s_barrier
	s_nop 0
	v_cmp_gt_i32_e32 vcc, s4, v8
	s_and_saveexec_b64 s[4:5], vcc
	s_cbranch_execz .LBB0_161
	v_lshlrev_b32_e32 v0, 4, v8
	v_mov_b32_e32 v6, v0
	s_add_u32 s8, s68, 0x2000
	s_addc_u32 s9, s69, 0
	global_load_dwordx4 v[12:15], v0, s[68:69]
	global_load_dwordx4 v[16:19], v0, s[8:9]
	global_load_dwordx4 v[20:23], v0, s[70:71]
	s_add_u32 s8, s58, 0x0
	s_addc_u32 s9, s59, 0
	global_load_dwordx4 v[24:27], v6, s[8:9]
	s_add_u32 s8, s58, 0x2000
	s_addc_u32 s9, s59, 0
	global_load_dwordx4 v[28:31], v6, s[8:9]
	s_add_u32 s8, s58, 0x18000
	s_addc_u32 s9, s59, 0
	global_load_dwordx4 v[32:35], v6, s[8:9]
	s_add_u32 s8, s58, 0x1a000
	s_addc_u32 s9, s59, 0
	global_load_dwordx4 v[36:39], v6, s[8:9]
	s_add_u32 s8, s58, 0x30000
	s_addc_u32 s9, s59, 0
	global_load_dwordx4 v[40:43], v6, s[8:9]
	s_add_u32 s8, s58, 0x32000
	s_addc_u32 s9, s59, 0
	global_load_dwordx4 v[44:47], v6, s[8:9]
	s_add_u32 s8, s58, 0x48000
	s_addc_u32 s9, s59, 0
	global_load_dwordx4 v[48:51], v6, s[8:9]
	s_add_u32 s8, s58, 0x4a000
	s_addc_u32 s9, s59, 0
	global_load_dwordx4 v[52:55], v6, s[8:9]
	s_add_u32 s8, s58, 0x60000
	s_addc_u32 s9, s59, 0
	global_load_dwordx4 v[56:59], v6, s[8:9]
	s_add_u32 s8, s58, 0x62000
	s_addc_u32 s9, s59, 0
	global_load_dwordx4 v[60:63], v6, s[8:9]
	s_add_u32 s8, s58, 0x78000
	s_addc_u32 s9, s59, 0
	global_load_dwordx4 v[64:67], v6, s[8:9]
	s_add_u32 s8, s58, 0x7a000
	s_addc_u32 s9, s59, 0
	global_load_dwordx4 v[68:71], v6, s[8:9]
	s_add_u32 s8, s58, 0x90000
	s_addc_u32 s9, s59, 0
	global_load_dwordx4 v[72:75], v6, s[8:9]
	s_add_u32 s8, s58, 0x92000
	s_addc_u32 s9, s59, 0
	global_load_dwordx4 v[76:79], v6, s[8:9]
	s_add_u32 s8, s58, 0xa8000
	s_addc_u32 s9, s59, 0
	global_load_dwordx4 v[80:83], v6, s[8:9]
	s_add_u32 s8, s58, 0xaa000
	s_addc_u32 s9, s59, 0
	global_load_dwordx4 v[84:87], v6, s[8:9]
	s_add_u32 s8, s58, 0xc0000
	s_addc_u32 s9, s59, 0
	global_load_dwordx4 v[88:91], v6, s[8:9]
	s_add_u32 s8, s58, 0xc2000
	s_addc_u32 s9, s59, 0
	global_load_dwordx4 v[92:95], v6, s[8:9]
	s_add_u32 s8, s58, 0xd8000
	s_addc_u32 s9, s59, 0
	global_load_dwordx4 v[96:99], v6, s[8:9]
	s_add_u32 s8, s58, 0xda000
	s_addc_u32 s9, s59, 0
	global_load_dwordx4 v[100:103], v6, s[8:9]
	s_add_u32 s8, s58, 0xf0000
	s_addc_u32 s9, s59, 0
	global_load_dwordx4 v[104:107], v6, s[8:9]
	s_add_u32 s8, s58, 0xf2000
	s_addc_u32 s9, s59, 0
	global_load_dwordx4 v[108:111], v6, s[8:9]
	s_add_u32 s8, s58, 0x108000
	s_addc_u32 s9, s59, 0
	global_load_dwordx4 v[112:115], v6, s[8:9]
	s_add_u32 s8, s58, 0x10a000
	s_addc_u32 s9, s59, 0
	global_load_dwordx4 v[116:119], v6, s[8:9]
	s_add_u32 s8, s58, 0x120000
	s_addc_u32 s9, s59, 0
	global_load_dwordx4 v[120:123], v6, s[8:9]
	s_add_u32 s8, s58, 0x122000
	s_addc_u32 s9, s59, 0
	global_load_dwordx4 v[132:135], v6, s[8:9]
	s_add_u32 s8, s58, 0x138000
	s_addc_u32 s9, s59, 0
	global_load_dwordx4 v[136:139], v6, s[8:9]
	s_add_u32 s8, s58, 0x13a000
	s_addc_u32 s9, s59, 0
	global_load_dwordx4 v[140:143], v6, s[8:9]
	s_add_u32 s8, s58, 0x150000
	s_addc_u32 s9, s59, 0
	global_load_dwordx4 v[144:147], v6, s[8:9]
	s_add_u32 s8, s58, 0x152000
	s_addc_u32 s9, s59, 0
	global_load_dwordx4 v[148:151], v6, s[8:9]
	s_add_u32 s8, s58, 0x168000
	s_addc_u32 s9, s59, 0
	global_load_dwordx4 v[152:155], v6, s[8:9]
	s_add_u32 s8, s58, 0x16a000
	s_addc_u32 s9, s59, 0
	global_load_dwordx4 v[156:159], v6, s[8:9]
	s_waitcnt vmcnt(30)
	v_pk_add_f32 v[12:13], v[12:13], v[24:25]
	v_pk_add_f32 v[14:15], v[14:15], v[26:27]
	v_pk_add_f32 v[16:17], v[16:17], v[28:29]
	v_pk_add_f32 v[18:19], v[18:19], v[30:31]
	s_waitcnt vmcnt(28)
	v_pk_add_f32 v[12:13], v[12:13], v[32:33]
	v_pk_add_f32 v[14:15], v[14:15], v[34:35]
	v_pk_add_f32 v[16:17], v[16:17], v[36:37]
	v_pk_add_f32 v[18:19], v[18:19], v[38:39]
	s_waitcnt vmcnt(26)
	v_pk_add_f32 v[12:13], v[12:13], v[40:41]
	v_pk_add_f32 v[14:15], v[14:15], v[42:43]
	v_pk_add_f32 v[16:17], v[16:17], v[44:45]
	v_pk_add_f32 v[18:19], v[18:19], v[46:47]
	s_waitcnt vmcnt(24)
	v_pk_add_f32 v[12:13], v[12:13], v[48:49]
	v_pk_add_f32 v[14:15], v[14:15], v[50:51]
	v_pk_add_f32 v[16:17], v[16:17], v[52:53]
	v_pk_add_f32 v[18:19], v[18:19], v[54:55]
	s_waitcnt vmcnt(22)
	v_pk_add_f32 v[12:13], v[12:13], v[56:57]
	v_pk_add_f32 v[14:15], v[14:15], v[58:59]
	v_pk_add_f32 v[16:17], v[16:17], v[60:61]
	v_pk_add_f32 v[18:19], v[18:19], v[62:63]
	s_waitcnt vmcnt(20)
	v_pk_add_f32 v[12:13], v[12:13], v[64:65]
	v_pk_add_f32 v[14:15], v[14:15], v[66:67]
	v_pk_add_f32 v[16:17], v[16:17], v[68:69]
	v_pk_add_f32 v[18:19], v[18:19], v[70:71]
	s_waitcnt vmcnt(18)
	v_pk_add_f32 v[12:13], v[12:13], v[72:73]
	v_pk_add_f32 v[14:15], v[14:15], v[74:75]
	v_pk_add_f32 v[16:17], v[16:17], v[76:77]
	v_pk_add_f32 v[18:19], v[18:19], v[78:79]
	s_waitcnt vmcnt(16)
	v_pk_add_f32 v[12:13], v[12:13], v[80:81]
	v_pk_add_f32 v[14:15], v[14:15], v[82:83]
	v_pk_add_f32 v[16:17], v[16:17], v[84:85]
	v_pk_add_f32 v[18:19], v[18:19], v[86:87]
	s_waitcnt vmcnt(14)
	v_pk_add_f32 v[12:13], v[12:13], v[88:89]
	v_pk_add_f32 v[14:15], v[14:15], v[90:91]
	v_pk_add_f32 v[16:17], v[16:17], v[92:93]
	v_pk_add_f32 v[18:19], v[18:19], v[94:95]
	s_waitcnt vmcnt(12)
	v_pk_add_f32 v[12:13], v[12:13], v[96:97]
	v_pk_add_f32 v[14:15], v[14:15], v[98:99]
	v_pk_add_f32 v[16:17], v[16:17], v[100:101]
	v_pk_add_f32 v[18:19], v[18:19], v[102:103]
	s_waitcnt vmcnt(10)
	v_pk_add_f32 v[12:13], v[12:13], v[104:105]
	v_pk_add_f32 v[14:15], v[14:15], v[106:107]
	v_pk_add_f32 v[16:17], v[16:17], v[108:109]
	v_pk_add_f32 v[18:19], v[18:19], v[110:111]
	s_waitcnt vmcnt(8)
; __device__ __forceinline__ void p1_rows(const Params& P, LAS unsigned char* lds, int G) {
;     ...
;     for (int idx = tid; idx < 2 * DM; idx += NTHREADS) { const int b = idx >> 11, col = idx & (DM - 1);
;         float sh = P.b_ada[col], sc = P.b_ada[DM + col];
;         for (int ks = 0; ks < KS_ADA; ++ks) { sh += adap[(size_t)(ks * 2 + b) * NADA + col]; sc += adap[(size_t)(ks * 2 + b) * NADA + DM + col]; }
;         TA[idx] = P.g_pre_mix[col] * (1.0f + sc); TC[idx] = sh; }
	v_pk_add_f32 v[12:13], v[12:13], v[112:113]
	v_pk_add_f32 v[14:15], v[14:15], v[114:115]
	v_pk_add_f32 v[16:17], v[16:17], v[116:117]
	v_pk_add_f32 v[18:19], v[18:19], v[118:119]
	s_waitcnt vmcnt(6)
	v_pk_add_f32 v[12:13], v[12:13], v[120:121]
	v_pk_add_f32 v[14:15], v[14:15], v[122:123]
	v_pk_add_f32 v[16:17], v[16:17], v[132:133]
	v_pk_add_f32 v[18:19], v[18:19], v[134:135]
	s_waitcnt vmcnt(4)
	v_pk_add_f32 v[12:13], v[12:13], v[136:137]
	v_pk_add_f32 v[14:15], v[14:15], v[138:139]
	v_pk_add_f32 v[16:17], v[16:17], v[140:141]
	v_pk_add_f32 v[18:19], v[18:19], v[142:143]
	s_waitcnt vmcnt(2)
	v_pk_add_f32 v[12:13], v[12:13], v[144:145]
	v_pk_add_f32 v[14:15], v[14:15], v[146:147]
	v_pk_add_f32 v[16:17], v[16:17], v[148:149]
	v_pk_add_f32 v[18:19], v[18:19], v[150:151]
	s_waitcnt vmcnt(0)
	v_pk_add_f32 v[12:13], v[12:13], v[152:153]
	v_pk_add_f32 v[14:15], v[14:15], v[154:155]
	v_pk_add_f32 v[16:17], v[16:17], v[156:157]
	v_pk_add_f32 v[18:19], v[18:19], v[158:159]
	v_add_f32_e32 v2, 1.0, v16
	v_add_f32_e32 v3, 1.0, v17
	v_add_f32_e32 v4, 1.0, v18
	v_add_f32_e32 v5, 1.0, v19
	v_mul_f32_e32 v2, v2, v20
	v_mul_f32_e32 v3, v3, v21
	v_mul_f32_e32 v4, v4, v22
	v_mul_f32_e32 v5, v5, v23
	v_mov_b32_e32 v7, v0
	ds_write_b128 v7, v[2:5]
	ds_write_b128 v7, v[12:15] offset:16384
	v_add_u32_e32 v6, 0xc000, v0
	s_add_u32 s8, s68, 0x2000
	s_addc_u32 s9, s69, 0
	global_load_dwordx4 v[12:15], v0, s[68:69]
	global_load_dwordx4 v[16:19], v0, s[8:9]
	global_load_dwordx4 v[20:23], v0, s[70:71]
	s_add_u32 s8, s58, 0x0
	s_addc_u32 s9, s59, 0
	global_load_dwordx4 v[24:27], v6, s[8:9]
	s_add_u32 s8, s58, 0x2000
	s_addc_u32 s9, s59, 0
	global_load_dwordx4 v[28:31], v6, s[8:9]
	s_add_u32 s8, s58, 0x18000
	s_addc_u32 s9, s59, 0
	global_load_dwordx4 v[32:35], v6, s[8:9]
	s_add_u32 s8, s58, 0x1a000
	s_addc_u32 s9, s59, 0
	global_load_dwordx4 v[36:39], v6, s[8:9]
	s_add_u32 s8, s58, 0x30000
	s_addc_u32 s9, s59, 0
	global_load_dwordx4 v[40:43], v6, s[8:9]
	s_add_u32 s8, s58, 0x32000
	s_addc_u32 s9, s59, 0
	global_load_dwordx4 v[44:47], v6, s[8:9]
	s_add_u32 s8, s58, 0x48000
	s_addc_u32 s9, s59, 0
	global_load_dwordx4 v[48:51], v6, s[8:9]
	s_add_u32 s8, s58, 0x4a000
	s_addc_u32 s9, s59, 0
	global_load_dwordx4 v[52:55], v6, s[8:9]
	s_add_u32 s8, s58, 0x60000
	s_addc_u32 s9, s59, 0
	global_load_dwordx4 v[56:59], v6, s[8:9]
	s_add_u32 s8, s58, 0x62000
	s_addc_u32 s9, s59, 0
	global_load_dwordx4 v[60:63], v6, s[8:9]
	s_add_u32 s8, s58, 0x78000
	s_addc_u32 s9, s59, 0
	global_load_dwordx4 v[64:67], v6, s[8:9]
	s_add_u32 s8, s58, 0x7a000
	s_addc_u32 s9, s59, 0
	global_load_dwordx4 v[68:71], v6, s[8:9]
	s_add_u32 s8, s58, 0x90000
	s_addc_u32 s9, s59, 0
	global_load_dwordx4 v[72:75], v6, s[8:9]
	s_add_u32 s8, s58, 0x92000
	s_addc_u32 s9, s59, 0
	global_load_dwordx4 v[76:79], v6, s[8:9]
	s_add_u32 s8, s58, 0xa8000
	s_addc_u32 s9, s59, 0
	global_load_dwordx4 v[80:83], v6, s[8:9]
	s_add_u32 s8, s58, 0xaa000
	s_addc_u32 s9, s59, 0
	global_load_dwordx4 v[84:87], v6, s[8:9]
	s_add_u32 s8, s58, 0xc0000
	s_addc_u32 s9, s59, 0
	global_load_dwordx4 v[88:91], v6, s[8:9]
	s_add_u32 s8, s58, 0xc2000
	s_addc_u32 s9, s59, 0
	global_load_dwordx4 v[92:95], v6, s[8:9]
	s_add_u32 s8, s58, 0xd8000
	s_addc_u32 s9, s59, 0
	global_load_dwordx4 v[96:99], v6, s[8:9]
	s_add_u32 s8, s58, 0xda000
	s_addc_u32 s9, s59, 0
	global_load_dwordx4 v[100:103], v6, s[8:9]
	s_add_u32 s8, s58, 0xf0000
	s_addc_u32 s9, s59, 0
	global_load_dwordx4 v[104:107], v6, s[8:9]
	s_add_u32 s8, s58, 0xf2000
	s_addc_u32 s9, s59, 0
	global_load_dwordx4 v[108:111], v6, s[8:9]
	s_add_u32 s8, s58, 0x108000
	s_addc_u32 s9, s59, 0
	global_load_dwordx4 v[112:115], v6, s[8:9]
	s_add_u32 s8, s58, 0x10a000
	s_addc_u32 s9, s59, 0
	global_load_dwordx4 v[116:119], v6, s[8:9]
	s_add_u32 s8, s58, 0x120000
	s_addc_u32 s9, s59, 0
	global_load_dwordx4 v[120:123], v6, s[8:9]
	s_add_u32 s8, s58, 0x122000
	s_addc_u32 s9, s59, 0
	global_load_dwordx4 v[132:135], v6, s[8:9]
	s_add_u32 s8, s58, 0x138000
	s_addc_u32 s9, s59, 0
	global_load_dwordx4 v[136:139], v6, s[8:9]
	s_add_u32 s8, s58, 0x13a000
	s_addc_u32 s9, s59, 0
	global_load_dwordx4 v[140:143], v6, s[8:9]
	s_add_u32 s8, s58, 0x150000
	s_addc_u32 s9, s59, 0
	global_load_dwordx4 v[144:147], v6, s[8:9]
	s_add_u32 s8, s58, 0x152000
	s_addc_u32 s9, s59, 0
	global_load_dwordx4 v[148:151], v6, s[8:9]
	s_add_u32 s8, s58, 0x168000
	s_addc_u32 s9, s59, 0
	global_load_dwordx4 v[152:155], v6, s[8:9]
	s_add_u32 s8, s58, 0x16a000
	s_addc_u32 s9, s59, 0
	global_load_dwordx4 v[156:159], v6, s[8:9]
	s_waitcnt vmcnt(30)
; __device__ __forceinline__ void p1_rows(const Params& P, LAS unsigned char* lds, int G) {
;     ...
;     for (int idx = tid; idx < 2 * DM; idx += NTHREADS) { const int b = idx >> 11, col = idx & (DM - 1);
;         float sh = P.b_ada[col], sc = P.b_ada[DM + col];
;         for (int ks = 0; ks < KS_ADA; ++ks) { sh += adap[(size_t)(ks * 2 + b) * NADA + col]; sc += adap[(size_t)(ks * 2 + b) * NADA + DM + col]; }
;         TA[idx] = P.g_pre_mix[col] * (1.0f + sc); TC[idx] = sh; }
	v_pk_add_f32 v[12:13], v[12:13], v[24:25]
	v_pk_add_f32 v[14:15], v[14:15], v[26:27]
	v_pk_add_f32 v[16:17], v[16:17], v[28:29]
	v_pk_add_f32 v[18:19], v[18:19], v[30:31]
	s_waitcnt vmcnt(28)
	v_pk_add_f32 v[12:13], v[12:13], v[32:33]
	v_pk_add_f32 v[14:15], v[14:15], v[34:35]
	v_pk_add_f32 v[16:17], v[16:17], v[36:37]
	v_pk_add_f32 v[18:19], v[18:19], v[38:39]
	s_waitcnt vmcnt(26)
	v_pk_add_f32 v[12:13], v[12:13], v[40:41]
	v_pk_add_f32 v[14:15], v[14:15], v[42:43]
	v_pk_add_f32 v[16:17], v[16:17], v[44:45]
	v_pk_add_f32 v[18:19], v[18:19], v[46:47]
	s_waitcnt vmcnt(24)
	v_pk_add_f32 v[12:13], v[12:13], v[48:49]
	v_pk_add_f32 v[14:15], v[14:15], v[50:51]
	v_pk_add_f32 v[16:17], v[16:17], v[52:53]
	v_pk_add_f32 v[18:19], v[18:19], v[54:55]
	s_waitcnt vmcnt(22)
	v_pk_add_f32 v[12:13], v[12:13], v[56:57]
	v_pk_add_f32 v[14:15], v[14:15], v[58:59]
	v_pk_add_f32 v[16:17], v[16:17], v[60:61]
	v_pk_add_f32 v[18:19], v[18:19], v[62:63]
	s_waitcnt vmcnt(20)
	v_pk_add_f32 v[12:13], v[12:13], v[64:65]
	v_pk_add_f32 v[14:15], v[14:15], v[66:67]
	v_pk_add_f32 v[16:17], v[16:17], v[68:69]
	v_pk_add_f32 v[18:19], v[18:19], v[70:71]
	s_waitcnt vmcnt(18)
	v_pk_add_f32 v[12:13], v[12:13], v[72:73]
	v_pk_add_f32 v[14:15], v[14:15], v[74:75]
	v_pk_add_f32 v[16:17], v[16:17], v[76:77]
	v_pk_add_f32 v[18:19], v[18:19], v[78:79]
	s_waitcnt vmcnt(16)
	v_pk_add_f32 v[12:13], v[12:13], v[80:81]
	v_pk_add_f32 v[14:15], v[14:15], v[82:83]
	v_pk_add_f32 v[16:17], v[16:17], v[84:85]
	v_pk_add_f32 v[18:19], v[18:19], v[86:87]
	s_waitcnt vmcnt(14)
	v_pk_add_f32 v[12:13], v[12:13], v[88:89]
	v_pk_add_f32 v[14:15], v[14:15], v[90:91]
	v_pk_add_f32 v[16:17], v[16:17], v[92:93]
	v_pk_add_f32 v[18:19], v[18:19], v[94:95]
	s_waitcnt vmcnt(12)
	v_pk_add_f32 v[12:13], v[12:13], v[96:97]
	v_pk_add_f32 v[14:15], v[14:15], v[98:99]
	v_pk_add_f32 v[16:17], v[16:17], v[100:101]
	v_pk_add_f32 v[18:19], v[18:19], v[102:103]
	s_waitcnt vmcnt(10)
	v_pk_add_f32 v[12:13], v[12:13], v[104:105]
	v_pk_add_f32 v[14:15], v[14:15], v[106:107]
	v_pk_add_f32 v[16:17], v[16:17], v[108:109]
	v_pk_add_f32 v[18:19], v[18:19], v[110:111]
	s_waitcnt vmcnt(8)
	v_pk_add_f32 v[12:13], v[12:13], v[112:113]
	v_pk_add_f32 v[14:15], v[14:15], v[114:115]
	v_pk_add_f32 v[16:17], v[16:17], v[116:117]
	v_pk_add_f32 v[18:19], v[18:19], v[118:119]
	s_waitcnt vmcnt(6)
	v_pk_add_f32 v[12:13], v[12:13], v[120:121]
	v_pk_add_f32 v[14:15], v[14:15], v[122:123]
	v_pk_add_f32 v[16:17], v[16:17], v[132:133]
	v_pk_add_f32 v[18:19], v[18:19], v[134:135]
	s_waitcnt vmcnt(4)
	v_pk_add_f32 v[12:13], v[12:13], v[136:137]
	v_pk_add_f32 v[14:15], v[14:15], v[138:139]
	v_pk_add_f32 v[16:17], v[16:17], v[140:141]
	v_pk_add_f32 v[18:19], v[18:19], v[142:143]
	s_waitcnt vmcnt(2)
	v_pk_add_f32 v[12:13], v[12:13], v[144:145]
	v_pk_add_f32 v[14:15], v[14:15], v[146:147]
	v_pk_add_f32 v[16:17], v[16:17], v[148:149]
	v_pk_add_f32 v[18:19], v[18:19], v[150:151]
	s_waitcnt vmcnt(0)
	v_pk_add_f32 v[12:13], v[12:13], v[152:153]
	v_pk_add_f32 v[14:15], v[14:15], v[154:155]
	v_pk_add_f32 v[16:17], v[16:17], v[156:157]
	v_pk_add_f32 v[18:19], v[18:19], v[158:159]
	v_add_f32_e32 v2, 1.0, v16
	v_add_f32_e32 v3, 1.0, v17
	v_add_f32_e32 v4, 1.0, v18
	v_add_f32_e32 v5, 1.0, v19
	v_mul_f32_e32 v2, v2, v20
	v_mul_f32_e32 v3, v3, v21
	v_mul_f32_e32 v4, v4, v22
	v_mul_f32_e32 v5, v5, v23
	v_add_u32_e32 v7, 0x2000, v0
	ds_write_b128 v7, v[2:5]
	ds_write_b128 v7, v[12:15] offset:16384
